# SwiGLU epilogue (FFN w13) rewritten by hand: staged packed f32 ops without dependent-issue fillers, exp2 scale folded into the per-row rstd, one SGPR-based store per row group
# speedup vs baseline: 1.0107x; 1.0107x over previous
.LBB0_318:
	s_andn2_b64 vcc, exec, s[0:1]
	s_cbranch_vccnz .LBB0_611
	s_mov_b64 s[0:1], -1
	s_cmp_gt_i32 s70, 0
	v_lshl_add_u32 v164, s76, 8, v178
	s_cbranch_scc0 .LBB0_321
	s_lshl_b32 s0, s7, 2
	s_add_i32 s68, s68, s0
	v_lshl_add_u32 v136, v155, 2, s68
	ds_read2_b32 v[128:129], v136 offset1:16
	ds_read2_b32 v[130:131], v136 offset0:32 offset1:48
	ds_read2_b32 v[132:133], v136 offset0:128 offset1:144
	ds_read2_b32 v[134:135], v136 offset0:160 offset1:176
	s_lshl_b32 s0, s72, 8
	s_lshl_b32 s2, s21, 1
	s_add_u32 s0, s0, s2
	s_add_u32 s0, s28, s0
	s_addc_u32 s1, s29, 0
	v_mul_u32_u24_e32 v137, 0x1600, v164
	v_lshl_add_u32 v137, v154, 1, v137
	v_mov_b32_e32 v166, 1.0
	s_waitcnt lgkmcnt(0)
	v_mov_b32_e32 v140, v128
	v_mul_f32_e32 v142, 0xbfb8aa3b, v128
	v_pk_mul_f32 v[168:169], v[124:125], v[142:143] op_sel_hi:[1,0]
	v_pk_mul_f32 v[170:171], v[126:127], v[142:143] op_sel_hi:[1,0]
	v_pk_mul_f32 v[172:173], v[120:121], v[142:143] op_sel_hi:[1,0]
	v_pk_mul_f32 v[174:175], v[122:123], v[142:143] op_sel_hi:[1,0]
	v_exp_f32_e32 v168, v168
	v_exp_f32_e32 v169, v169
	v_exp_f32_e32 v170, v170
	v_exp_f32_e32 v171, v171
	v_exp_f32_e32 v172, v172
	v_exp_f32_e32 v173, v173
	v_exp_f32_e32 v174, v174
	v_exp_f32_e32 v175, v175
	v_pk_mul_f32 v[124:125], v[124:125], v[140:141] op_sel_hi:[1,0]
	v_pk_mul_f32 v[126:127], v[126:127], v[140:141] op_sel_hi:[1,0]
	v_pk_mul_f32 v[120:121], v[120:121], v[140:141] op_sel_hi:[1,0]
	v_pk_mul_f32 v[122:123], v[122:123], v[140:141] op_sel_hi:[1,0]
	v_pk_add_f32 v[168:169], v[168:169], v[166:167] op_sel_hi:[1,0]
	v_pk_add_f32 v[170:171], v[170:171], v[166:167] op_sel_hi:[1,0]
	v_pk_add_f32 v[172:173], v[172:173], v[166:167] op_sel_hi:[1,0]
	v_pk_add_f32 v[174:175], v[174:175], v[166:167] op_sel_hi:[1,0]
	v_rcp_f32_e32 v168, v168
	v_rcp_f32_e32 v169, v169
	v_rcp_f32_e32 v170, v170
	v_rcp_f32_e32 v171, v171
	v_rcp_f32_e32 v172, v172
	v_rcp_f32_e32 v173, v173
	v_rcp_f32_e32 v174, v174
	v_rcp_f32_e32 v175, v175
	v_pk_mul_f32 v[92:93], v[92:93], v[140:141] op_sel_hi:[1,0]
	v_pk_mul_f32 v[94:95], v[94:95], v[140:141] op_sel_hi:[1,0]
	v_pk_mul_f32 v[88:89], v[88:89], v[140:141] op_sel_hi:[1,0]
	v_pk_mul_f32 v[90:91], v[90:91], v[140:141] op_sel_hi:[1,0]
	v_pk_mul_f32 v[124:125], v[124:125], v[168:169]
	v_pk_mul_f32 v[126:127], v[126:127], v[170:171]
	v_pk_mul_f32 v[120:121], v[120:121], v[172:173]
	v_pk_mul_f32 v[122:123], v[122:123], v[174:175]
	v_pk_mul_f32 v[124:125], v[92:93], v[124:125]
	v_pk_mul_f32 v[126:127], v[94:95], v[126:127]
	v_pk_mul_f32 v[120:121], v[88:89], v[120:121]
	v_pk_mul_f32 v[122:123], v[90:91], v[122:123]
	v_cvt_pk_bf16_f32 v168, v124, v125
	v_cvt_pk_bf16_f32 v169, v126, v127
	v_cvt_pk_bf16_f32 v170, v120, v121
	v_cvt_pk_bf16_f32 v171, v122, v123
	global_store_dwordx4 v137, v[168:171], s[0:1]
	s_add_u32 s0, s0, 0x16000
	s_addc_u32 s1, s1, 0
	v_mov_b32_e32 v140, v129
	v_mul_f32_e32 v142, 0xbfb8aa3b, v129
	v_pk_mul_f32 v[184:185], v[116:117], v[142:143] op_sel_hi:[1,0]
	v_pk_mul_f32 v[186:187], v[118:119], v[142:143] op_sel_hi:[1,0]
	v_pk_mul_f32 v[188:189], v[112:113], v[142:143] op_sel_hi:[1,0]
	v_pk_mul_f32 v[190:191], v[114:115], v[142:143] op_sel_hi:[1,0]
	v_exp_f32_e32 v184, v184
	v_exp_f32_e32 v185, v185
	v_exp_f32_e32 v186, v186
	v_exp_f32_e32 v187, v187
	v_exp_f32_e32 v188, v188
	v_exp_f32_e32 v189, v189
	v_exp_f32_e32 v190, v190
	v_exp_f32_e32 v191, v191
	v_pk_mul_f32 v[116:117], v[116:117], v[140:141] op_sel_hi:[1,0]
	v_pk_mul_f32 v[118:119], v[118:119], v[140:141] op_sel_hi:[1,0]
	v_pk_mul_f32 v[112:113], v[112:113], v[140:141] op_sel_hi:[1,0]
	v_pk_mul_f32 v[114:115], v[114:115], v[140:141] op_sel_hi:[1,0]
	v_pk_add_f32 v[184:185], v[184:185], v[166:167] op_sel_hi:[1,0]
	v_pk_add_f32 v[186:187], v[186:187], v[166:167] op_sel_hi:[1,0]
	v_pk_add_f32 v[188:189], v[188:189], v[166:167] op_sel_hi:[1,0]
	v_pk_add_f32 v[190:191], v[190:191], v[166:167] op_sel_hi:[1,0]
	v_rcp_f32_e32 v184, v184
	v_rcp_f32_e32 v185, v185
	v_rcp_f32_e32 v186, v186
	v_rcp_f32_e32 v187, v187
	v_rcp_f32_e32 v188, v188
	v_rcp_f32_e32 v189, v189
	v_rcp_f32_e32 v190, v190
	v_rcp_f32_e32 v191, v191
	v_pk_mul_f32 v[84:85], v[84:85], v[140:141] op_sel_hi:[1,0]
	v_pk_mul_f32 v[86:87], v[86:87], v[140:141] op_sel_hi:[1,0]
	v_pk_mul_f32 v[80:81], v[80:81], v[140:141] op_sel_hi:[1,0]
	v_pk_mul_f32 v[82:83], v[82:83], v[140:141] op_sel_hi:[1,0]
	v_pk_mul_f32 v[116:117], v[116:117], v[184:185]
	v_pk_mul_f32 v[118:119], v[118:119], v[186:187]
	v_pk_mul_f32 v[112:113], v[112:113], v[188:189]
	v_pk_mul_f32 v[114:115], v[114:115], v[190:191]
	v_pk_mul_f32 v[116:117], v[84:85], v[116:117]
	v_pk_mul_f32 v[118:119], v[86:87], v[118:119]
	v_pk_mul_f32 v[112:113], v[80:81], v[112:113]
	v_pk_mul_f32 v[114:115], v[82:83], v[114:115]
	v_cvt_pk_bf16_f32 v184, v116, v117
	v_cvt_pk_bf16_f32 v185, v118, v119
	v_cvt_pk_bf16_f32 v186, v112, v113
	v_cvt_pk_bf16_f32 v187, v114, v115
	global_store_dwordx4 v137, v[184:187], s[0:1]
	s_add_u32 s0, s0, 0x16000
	s_addc_u32 s1, s1, 0
	v_mov_b32_e32 v140, v130
	v_mul_f32_e32 v142, 0xbfb8aa3b, v130
	v_pk_mul_f32 v[168:169], v[108:109], v[142:143] op_sel_hi:[1,0]
	v_pk_mul_f32 v[170:171], v[110:111], v[142:143] op_sel_hi:[1,0]
	v_pk_mul_f32 v[172:173], v[104:105], v[142:143] op_sel_hi:[1,0]
	v_pk_mul_f32 v[174:175], v[106:107], v[142:143] op_sel_hi:[1,0]
	v_exp_f32_e32 v168, v168
	v_exp_f32_e32 v169, v169
	v_exp_f32_e32 v170, v170
	v_exp_f32_e32 v171, v171
	v_exp_f32_e32 v172, v172
	v_exp_f32_e32 v173, v173
	v_exp_f32_e32 v174, v174
	v_exp_f32_e32 v175, v175
	v_pk_mul_f32 v[108:109], v[108:109], v[140:141] op_sel_hi:[1,0]
	v_pk_mul_f32 v[110:111], v[110:111], v[140:141] op_sel_hi:[1,0]
	v_pk_mul_f32 v[104:105], v[104:105], v[140:141] op_sel_hi:[1,0]
	v_pk_mul_f32 v[106:107], v[106:107], v[140:141] op_sel_hi:[1,0]
	v_pk_add_f32 v[168:169], v[168:169], v[166:167] op_sel_hi:[1,0]
	v_pk_add_f32 v[170:171], v[170:171], v[166:167] op_sel_hi:[1,0]
	v_pk_add_f32 v[172:173], v[172:173], v[166:167] op_sel_hi:[1,0]
	v_pk_add_f32 v[174:175], v[174:175], v[166:167] op_sel_hi:[1,0]
	v_rcp_f32_e32 v168, v168
	v_rcp_f32_e32 v169, v169
	v_rcp_f32_e32 v170, v170
	v_rcp_f32_e32 v171, v171
	v_rcp_f32_e32 v172, v172
	v_rcp_f32_e32 v173, v173
	v_rcp_f32_e32 v174, v174
	v_rcp_f32_e32 v175, v175
	v_pk_mul_f32 v[76:77], v[76:77], v[140:141] op_sel_hi:[1,0]
	v_pk_mul_f32 v[78:79], v[78:79], v[140:141] op_sel_hi:[1,0]
	v_pk_mul_f32 v[72:73], v[72:73], v[140:141] op_sel_hi:[1,0]
	v_pk_mul_f32 v[74:75], v[74:75], v[140:141] op_sel_hi:[1,0]
	v_pk_mul_f32 v[108:109], v[108:109], v[168:169]
	v_pk_mul_f32 v[110:111], v[110:111], v[170:171]
	v_pk_mul_f32 v[104:105], v[104:105], v[172:173]
	v_pk_mul_f32 v[106:107], v[106:107], v[174:175]
	v_pk_mul_f32 v[108:109], v[76:77], v[108:109]
	v_pk_mul_f32 v[110:111], v[78:79], v[110:111]
	v_pk_mul_f32 v[104:105], v[72:73], v[104:105]
	v_pk_mul_f32 v[106:107], v[74:75], v[106:107]
	v_cvt_pk_bf16_f32 v168, v108, v109
	v_cvt_pk_bf16_f32 v169, v110, v111
	v_cvt_pk_bf16_f32 v170, v104, v105
	v_cvt_pk_bf16_f32 v171, v106, v107
	global_store_dwordx4 v137, v[168:171], s[0:1]
	s_add_u32 s0, s0, 0x16000
	s_addc_u32 s1, s1, 0
	v_mov_b32_e32 v140, v131
	v_mul_f32_e32 v142, 0xbfb8aa3b, v131
	v_pk_mul_f32 v[184:185], v[100:101], v[142:143] op_sel_hi:[1,0]
	v_pk_mul_f32 v[186:187], v[102:103], v[142:143] op_sel_hi:[1,0]
	v_pk_mul_f32 v[188:189], v[96:97], v[142:143] op_sel_hi:[1,0]
	v_pk_mul_f32 v[190:191], v[98:99], v[142:143] op_sel_hi:[1,0]
	v_exp_f32_e32 v184, v184
	v_exp_f32_e32 v185, v185
	v_exp_f32_e32 v186, v186
	v_exp_f32_e32 v187, v187
	v_exp_f32_e32 v188, v188
	v_exp_f32_e32 v189, v189
	v_exp_f32_e32 v190, v190
	v_exp_f32_e32 v191, v191
	v_pk_mul_f32 v[100:101], v[100:101], v[140:141] op_sel_hi:[1,0]
	v_pk_mul_f32 v[102:103], v[102:103], v[140:141] op_sel_hi:[1,0]
	v_pk_mul_f32 v[96:97], v[96:97], v[140:141] op_sel_hi:[1,0]
	v_pk_mul_f32 v[98:99], v[98:99], v[140:141] op_sel_hi:[1,0]
	v_pk_add_f32 v[184:185], v[184:185], v[166:167] op_sel_hi:[1,0]
	v_pk_add_f32 v[186:187], v[186:187], v[166:167] op_sel_hi:[1,0]
	v_pk_add_f32 v[188:189], v[188:189], v[166:167] op_sel_hi:[1,0]
	v_pk_add_f32 v[190:191], v[190:191], v[166:167] op_sel_hi:[1,0]
	v_rcp_f32_e32 v184, v184
	v_rcp_f32_e32 v185, v185
	v_rcp_f32_e32 v186, v186
	v_rcp_f32_e32 v187, v187
	v_rcp_f32_e32 v188, v188
	v_rcp_f32_e32 v189, v189
	v_rcp_f32_e32 v190, v190
	v_rcp_f32_e32 v191, v191
	v_pk_mul_f32 v[68:69], v[68:69], v[140:141] op_sel_hi:[1,0]
	v_pk_mul_f32 v[70:71], v[70:71], v[140:141] op_sel_hi:[1,0]
	v_pk_mul_f32 v[64:65], v[64:65], v[140:141] op_sel_hi:[1,0]
	v_pk_mul_f32 v[66:67], v[66:67], v[140:141] op_sel_hi:[1,0]
	v_pk_mul_f32 v[100:101], v[100:101], v[184:185]
	v_pk_mul_f32 v[102:103], v[102:103], v[186:187]
	v_pk_mul_f32 v[96:97], v[96:97], v[188:189]
	v_pk_mul_f32 v[98:99], v[98:99], v[190:191]
	v_pk_mul_f32 v[100:101], v[68:69], v[100:101]
	v_pk_mul_f32 v[102:103], v[70:71], v[102:103]
	v_pk_mul_f32 v[96:97], v[64:65], v[96:97]
	v_pk_mul_f32 v[98:99], v[66:67], v[98:99]
	v_cvt_pk_bf16_f32 v184, v100, v101
	v_cvt_pk_bf16_f32 v185, v102, v103
	v_cvt_pk_bf16_f32 v186, v96, v97
	v_cvt_pk_bf16_f32 v187, v98, v99
	global_store_dwordx4 v137, v[184:187], s[0:1]
	s_add_u32 s0, s0, 0x6e000
	s_addc_u32 s1, s1, 0
	v_mov_b32_e32 v140, v132
	v_mul_f32_e32 v142, 0xbfb8aa3b, v132
	v_pk_mul_f32 v[168:169], v[60:61], v[142:143] op_sel_hi:[1,0]
	v_pk_mul_f32 v[170:171], v[62:63], v[142:143] op_sel_hi:[1,0]
	v_pk_mul_f32 v[172:173], v[56:57], v[142:143] op_sel_hi:[1,0]
	v_pk_mul_f32 v[174:175], v[58:59], v[142:143] op_sel_hi:[1,0]
	v_exp_f32_e32 v168, v168
	v_exp_f32_e32 v169, v169
	v_exp_f32_e32 v170, v170
	v_exp_f32_e32 v171, v171
	v_exp_f32_e32 v172, v172
	v_exp_f32_e32 v173, v173
	v_exp_f32_e32 v174, v174
	v_exp_f32_e32 v175, v175
	v_pk_mul_f32 v[60:61], v[60:61], v[140:141] op_sel_hi:[1,0]
	v_pk_mul_f32 v[62:63], v[62:63], v[140:141] op_sel_hi:[1,0]
	v_pk_mul_f32 v[56:57], v[56:57], v[140:141] op_sel_hi:[1,0]
	v_pk_mul_f32 v[58:59], v[58:59], v[140:141] op_sel_hi:[1,0]
	v_pk_add_f32 v[168:169], v[168:169], v[166:167] op_sel_hi:[1,0]
	v_pk_add_f32 v[170:171], v[170:171], v[166:167] op_sel_hi:[1,0]
	v_pk_add_f32 v[172:173], v[172:173], v[166:167] op_sel_hi:[1,0]
	v_pk_add_f32 v[174:175], v[174:175], v[166:167] op_sel_hi:[1,0]
	v_rcp_f32_e32 v168, v168
	v_rcp_f32_e32 v169, v169
	v_rcp_f32_e32 v170, v170
	v_rcp_f32_e32 v171, v171
	v_rcp_f32_e32 v172, v172
	v_rcp_f32_e32 v173, v173
	v_rcp_f32_e32 v174, v174
	v_rcp_f32_e32 v175, v175
	v_pk_mul_f32 v[28:29], v[28:29], v[140:141] op_sel_hi:[1,0]
	v_pk_mul_f32 v[30:31], v[30:31], v[140:141] op_sel_hi:[1,0]
	v_pk_mul_f32 v[24:25], v[24:25], v[140:141] op_sel_hi:[1,0]
	v_pk_mul_f32 v[26:27], v[26:27], v[140:141] op_sel_hi:[1,0]
	v_pk_mul_f32 v[60:61], v[60:61], v[168:169]
	v_pk_mul_f32 v[62:63], v[62:63], v[170:171]
	v_pk_mul_f32 v[56:57], v[56:57], v[172:173]
	v_pk_mul_f32 v[58:59], v[58:59], v[174:175]
	v_pk_mul_f32 v[60:61], v[28:29], v[60:61]
	v_pk_mul_f32 v[62:63], v[30:31], v[62:63]
	v_pk_mul_f32 v[56:57], v[24:25], v[56:57]
	v_pk_mul_f32 v[58:59], v[26:27], v[58:59]
	v_cvt_pk_bf16_f32 v168, v60, v61
	v_cvt_pk_bf16_f32 v169, v62, v63
	v_cvt_pk_bf16_f32 v170, v56, v57
	v_cvt_pk_bf16_f32 v171, v58, v59
	global_store_dwordx4 v137, v[168:171], s[0:1]
	s_add_u32 s0, s0, 0x16000
	s_addc_u32 s1, s1, 0
	v_mov_b32_e32 v140, v133
	v_mul_f32_e32 v142, 0xbfb8aa3b, v133
	v_pk_mul_f32 v[184:185], v[52:53], v[142:143] op_sel_hi:[1,0]
	v_pk_mul_f32 v[186:187], v[54:55], v[142:143] op_sel_hi:[1,0]
	v_pk_mul_f32 v[188:189], v[48:49], v[142:143] op_sel_hi:[1,0]
	v_pk_mul_f32 v[190:191], v[50:51], v[142:143] op_sel_hi:[1,0]
	v_exp_f32_e32 v184, v184
	v_exp_f32_e32 v185, v185
	v_exp_f32_e32 v186, v186
	v_exp_f32_e32 v187, v187
	v_exp_f32_e32 v188, v188
	v_exp_f32_e32 v189, v189
	v_exp_f32_e32 v190, v190
	v_exp_f32_e32 v191, v191
	v_pk_mul_f32 v[52:53], v[52:53], v[140:141] op_sel_hi:[1,0]
	v_pk_mul_f32 v[54:55], v[54:55], v[140:141] op_sel_hi:[1,0]
	v_pk_mul_f32 v[48:49], v[48:49], v[140:141] op_sel_hi:[1,0]
	v_pk_mul_f32 v[50:51], v[50:51], v[140:141] op_sel_hi:[1,0]
	v_pk_add_f32 v[184:185], v[184:185], v[166:167] op_sel_hi:[1,0]
	v_pk_add_f32 v[186:187], v[186:187], v[166:167] op_sel_hi:[1,0]
	v_pk_add_f32 v[188:189], v[188:189], v[166:167] op_sel_hi:[1,0]
	v_pk_add_f32 v[190:191], v[190:191], v[166:167] op_sel_hi:[1,0]
	v_rcp_f32_e32 v184, v184
	v_rcp_f32_e32 v185, v185
	v_rcp_f32_e32 v186, v186
	v_rcp_f32_e32 v187, v187
	v_rcp_f32_e32 v188, v188
	v_rcp_f32_e32 v189, v189
	v_rcp_f32_e32 v190, v190
	v_rcp_f32_e32 v191, v191
	v_pk_mul_f32 v[20:21], v[20:21], v[140:141] op_sel_hi:[1,0]
	v_pk_mul_f32 v[22:23], v[22:23], v[140:141] op_sel_hi:[1,0]
	v_pk_mul_f32 v[16:17], v[16:17], v[140:141] op_sel_hi:[1,0]
	v_pk_mul_f32 v[18:19], v[18:19], v[140:141] op_sel_hi:[1,0]
	v_pk_mul_f32 v[52:53], v[52:53], v[184:185]
	v_pk_mul_f32 v[54:55], v[54:55], v[186:187]
	v_pk_mul_f32 v[48:49], v[48:49], v[188:189]
	v_pk_mul_f32 v[50:51], v[50:51], v[190:191]
	v_pk_mul_f32 v[52:53], v[20:21], v[52:53]
	v_pk_mul_f32 v[54:55], v[22:23], v[54:55]
	v_pk_mul_f32 v[48:49], v[16:17], v[48:49]
	v_pk_mul_f32 v[50:51], v[18:19], v[50:51]
	v_cvt_pk_bf16_f32 v184, v52, v53
	v_cvt_pk_bf16_f32 v185, v54, v55
	v_cvt_pk_bf16_f32 v186, v48, v49
	v_cvt_pk_bf16_f32 v187, v50, v51
	global_store_dwordx4 v137, v[184:187], s[0:1]
	s_add_u32 s0, s0, 0x16000
	s_addc_u32 s1, s1, 0
	v_mov_b32_e32 v140, v134
	v_mul_f32_e32 v142, 0xbfb8aa3b, v134
	v_pk_mul_f32 v[168:169], v[44:45], v[142:143] op_sel_hi:[1,0]
	v_pk_mul_f32 v[170:171], v[46:47], v[142:143] op_sel_hi:[1,0]
	v_pk_mul_f32 v[172:173], v[40:41], v[142:143] op_sel_hi:[1,0]
	v_pk_mul_f32 v[174:175], v[42:43], v[142:143] op_sel_hi:[1,0]
	v_exp_f32_e32 v168, v168
	v_exp_f32_e32 v169, v169
	v_exp_f32_e32 v170, v170
	v_exp_f32_e32 v171, v171
	v_exp_f32_e32 v172, v172
	v_exp_f32_e32 v173, v173
	v_exp_f32_e32 v174, v174
	v_exp_f32_e32 v175, v175
	v_pk_mul_f32 v[44:45], v[44:45], v[140:141] op_sel_hi:[1,0]
	v_pk_mul_f32 v[46:47], v[46:47], v[140:141] op_sel_hi:[1,0]
	v_pk_mul_f32 v[40:41], v[40:41], v[140:141] op_sel_hi:[1,0]
	v_pk_mul_f32 v[42:43], v[42:43], v[140:141] op_sel_hi:[1,0]
	v_pk_add_f32 v[168:169], v[168:169], v[166:167] op_sel_hi:[1,0]
	v_pk_add_f32 v[170:171], v[170:171], v[166:167] op_sel_hi:[1,0]
	v_pk_add_f32 v[172:173], v[172:173], v[166:167] op_sel_hi:[1,0]
	v_pk_add_f32 v[174:175], v[174:175], v[166:167] op_sel_hi:[1,0]
	v_rcp_f32_e32 v168, v168
	v_rcp_f32_e32 v169, v169
	v_rcp_f32_e32 v170, v170
	v_rcp_f32_e32 v171, v171
	v_rcp_f32_e32 v172, v172
	v_rcp_f32_e32 v173, v173
	v_rcp_f32_e32 v174, v174
	v_rcp_f32_e32 v175, v175
	v_pk_mul_f32 v[12:13], v[12:13], v[140:141] op_sel_hi:[1,0]
	v_pk_mul_f32 v[14:15], v[14:15], v[140:141] op_sel_hi:[1,0]
	v_pk_mul_f32 v[8:9], v[8:9], v[140:141] op_sel_hi:[1,0]
	v_pk_mul_f32 v[10:11], v[10:11], v[140:141] op_sel_hi:[1,0]
	v_pk_mul_f32 v[44:45], v[44:45], v[168:169]
	v_pk_mul_f32 v[46:47], v[46:47], v[170:171]
	v_pk_mul_f32 v[40:41], v[40:41], v[172:173]
	v_pk_mul_f32 v[42:43], v[42:43], v[174:175]
	v_pk_mul_f32 v[44:45], v[12:13], v[44:45]
	v_pk_mul_f32 v[46:47], v[14:15], v[46:47]
	v_pk_mul_f32 v[40:41], v[8:9], v[40:41]
	v_pk_mul_f32 v[42:43], v[10:11], v[42:43]
	v_cvt_pk_bf16_f32 v168, v44, v45
	v_cvt_pk_bf16_f32 v169, v46, v47
	v_cvt_pk_bf16_f32 v170, v40, v41
	v_cvt_pk_bf16_f32 v171, v42, v43
	global_store_dwordx4 v137, v[168:171], s[0:1]
	s_add_u32 s0, s0, 0x16000
	s_addc_u32 s1, s1, 0
	v_mov_b32_e32 v140, v135
	v_mul_f32_e32 v142, 0xbfb8aa3b, v135
	v_pk_mul_f32 v[184:185], v[36:37], v[142:143] op_sel_hi:[1,0]
	v_pk_mul_f32 v[186:187], v[38:39], v[142:143] op_sel_hi:[1,0]
	v_pk_mul_f32 v[188:189], v[32:33], v[142:143] op_sel_hi:[1,0]
	v_pk_mul_f32 v[190:191], v[34:35], v[142:143] op_sel_hi:[1,0]
	v_exp_f32_e32 v184, v184
	v_exp_f32_e32 v185, v185
	v_exp_f32_e32 v186, v186
	v_exp_f32_e32 v187, v187
	v_exp_f32_e32 v188, v188
	v_exp_f32_e32 v189, v189
	v_exp_f32_e32 v190, v190
	v_exp_f32_e32 v191, v191
	v_pk_mul_f32 v[36:37], v[36:37], v[140:141] op_sel_hi:[1,0]
	v_pk_mul_f32 v[38:39], v[38:39], v[140:141] op_sel_hi:[1,0]
	v_pk_mul_f32 v[32:33], v[32:33], v[140:141] op_sel_hi:[1,0]
	v_pk_mul_f32 v[34:35], v[34:35], v[140:141] op_sel_hi:[1,0]
	v_pk_add_f32 v[184:185], v[184:185], v[166:167] op_sel_hi:[1,0]
	v_pk_add_f32 v[186:187], v[186:187], v[166:167] op_sel_hi:[1,0]
	v_pk_add_f32 v[188:189], v[188:189], v[166:167] op_sel_hi:[1,0]
	v_pk_add_f32 v[190:191], v[190:191], v[166:167] op_sel_hi:[1,0]
	v_rcp_f32_e32 v184, v184
	v_rcp_f32_e32 v185, v185
	v_rcp_f32_e32 v186, v186
	v_rcp_f32_e32 v187, v187
	v_rcp_f32_e32 v188, v188
	v_rcp_f32_e32 v189, v189
	v_rcp_f32_e32 v190, v190
	v_rcp_f32_e32 v191, v191
	v_pk_mul_f32 v[4:5], v[4:5], v[140:141] op_sel_hi:[1,0]
	v_pk_mul_f32 v[6:7], v[6:7], v[140:141] op_sel_hi:[1,0]
	v_pk_mul_f32 v[0:1], v[0:1], v[140:141] op_sel_hi:[1,0]
	v_pk_mul_f32 v[2:3], v[2:3], v[140:141] op_sel_hi:[1,0]
	v_pk_mul_f32 v[36:37], v[36:37], v[184:185]
	v_pk_mul_f32 v[38:39], v[38:39], v[186:187]
	v_pk_mul_f32 v[32:33], v[32:33], v[188:189]
	v_pk_mul_f32 v[34:35], v[34:35], v[190:191]
	v_pk_mul_f32 v[36:37], v[4:5], v[36:37]
	v_pk_mul_f32 v[38:39], v[6:7], v[38:39]
	v_pk_mul_f32 v[32:33], v[0:1], v[32:33]
	v_pk_mul_f32 v[34:35], v[2:3], v[34:35]
	v_cvt_pk_bf16_f32 v184, v36, v37
	v_cvt_pk_bf16_f32 v185, v38, v39
	v_cvt_pk_bf16_f32 v186, v32, v33
	v_cvt_pk_bf16_f32 v187, v34, v35
	global_store_dwordx4 v137, v[184:187], s[0:1]
	s_mov_b64 s[0:1], 0
